# attention q fragment loads issued in the shadow of the K/V staging, on top of the ss LDS-DMA + hand-scheduled mLSTM version
# baseline (speedup 1.0000x reference)
.LBB0_346:
	s_ashr_i32 s6, s78, 9
	s_lshl_b32 s9, s6, 1
	s_lshr_b32 s4, 64, s9
	s_and_b32 s1, s78, 63
	s_sub_i32 s8, 6, s9
	s_add_i32 s4, s4, -1
	s_mul_i32 s24, s6, 0xc00
	s_lshr_b32 s8, s1, s8
	s_and_b32 s1, s4, s1
	s_ashr_i32 s25, s24, 31
	s_bfe_u32 s79, s78, 0x30006
	s_lshr_b32 s7, 0x2000, s9
	s_lshl_b32 s22, s1, 7
	s_lshl_b64 s[24:25], s[24:25], 1
	s_add_u32 s1, s17, s24
	s_addc_u32 s23, s20, s25
	s_lshl_b32 s4, s79, 8
	s_add_u32 s24, s1, s4
	s_addc_u32 s25, s23, 0
	s_add_u32 s26, s24, 0x1000
	s_addc_u32 s27, s25, 0
	s_sub_i32 s23, s22, 64
	v_add_u32_e32 v2, s23, v13
	v_cmp_lt_i32_e32 vcc, -1, v2
	v_cmp_gt_i32_e64 s[62:63], s7, v2
	s_and_b64 vcc, vcc, s[62:63]
	v_cndmask_b32_e32 v2, 0, v2, vcc
	v_lshlrev_b32_e32 v2, s9, v2
	v_add_u32_e32 v2, s8, v2
	v_mad_u64_u32 v[2:3], s[62:63], v2, s94, 0
	v_add_u32_e32 v23, s23, v33
	v_cmp_lt_i32_e64 s[62:63], -1, v23
	v_cmp_gt_i32_e64 s[64:65], s7, v23
	s_and_b64 s[62:63], s[62:63], s[64:65]
	v_cndmask_b32_e64 v23, 0, v23, s[62:63]
	v_lshlrev_b32_e32 v23, s9, v23
	v_add_u32_e32 v23, s8, v23
	v_mad_u64_u32 v[24:25], s[64:65], v23, s94, 0
	v_add_u32_e32 v23, s23, v34
	v_cmp_lt_i32_e64 s[64:65], -1, v23
	v_cmp_gt_i32_e64 s[66:67], s7, v23
	s_and_b64 s[64:65], s[64:65], s[66:67]
	v_cndmask_b32_e64 v23, 0, v23, s[64:65]
	v_lshlrev_b32_e32 v23, s9, v23
	v_add_u32_e32 v23, s8, v23
	v_mad_u64_u32 v[160:161], s[66:67], v23, s94, 0
	v_add_u32_e32 v23, s23, v35
	v_cmp_lt_i32_e64 s[66:67], -1, v23
	v_cmp_gt_i32_e64 s[68:69], s7, v23
	s_and_b64 s[66:67], s[66:67], s[68:69]
	v_or_b32_e32 v2, v2, v10
	v_or_b32_e32 v24, v24, v10
	v_or_b32_e32 v160, v160, v10
	v_cndmask_b32_e64 v23, 0, v23, s[66:67]
	v_lshlrev_b64 v[2:3], 1, v[2:3]
	v_lshlrev_b64 v[24:25], 1, v[24:25]
	v_lshlrev_b64 v[160:161], 1, v[160:161]
	v_lshlrev_b32_e32 v23, s9, v23
	v_lshl_add_u64 v[4:5], s[24:25], 0, v[2:3]
	v_lshl_add_u64 v[6:7], s[26:27], 0, v[2:3]
	v_lshl_add_u64 v[26:27], s[24:25], 0, v[24:25]
	v_lshl_add_u64 v[156:157], s[26:27], 0, v[24:25]
	v_lshl_add_u64 v[176:177], s[24:25], 0, v[160:161]
	v_lshl_add_u64 v[160:161], s[26:27], 0, v[160:161]
	v_add_u32_e32 v23, s8, v23
	global_load_dwordx4 v[2:5], v[4:5], off offset:2048
	s_nop 0
	global_load_dwordx4 v[6:9], v[6:7], off
	s_nop 0
	global_load_dwordx4 v[24:27], v[26:27], off offset:2048
	s_nop 0
	global_load_dwordx4 v[156:159], v[156:157], off
	s_nop 0
	global_load_dwordx4 v[178:181], v[176:177], off offset:2048
	global_load_dwordx4 v[182:185], v[160:161], off
	v_mad_u64_u32 v[160:161], s[68:69], v23, s94, 0
	v_add_u32_e32 v23, s23, v36
	v_cmp_lt_i32_e64 s[68:69], -1, v23
	v_cmp_gt_i32_e64 s[70:71], s7, v23
	s_and_b64 s[68:69], s[68:69], s[70:71]
	v_or_b32_e32 v160, v160, v10
	v_cndmask_b32_e64 v23, 0, v23, s[68:69]
	v_lshlrev_b64 v[160:161], 1, v[160:161]
	v_lshlrev_b32_e32 v23, s9, v23
	v_lshl_add_u64 v[176:177], s[24:25], 0, v[160:161]
	v_lshl_add_u64 v[160:161], s[26:27], 0, v[160:161]
	v_add_u32_e32 v23, s8, v23
	global_load_dwordx4 v[186:189], v[176:177], off offset:2048
	global_load_dwordx4 v[190:193], v[160:161], off
	v_mad_u64_u32 v[160:161], s[70:71], v23, s94, 0
	v_add_u32_e32 v23, s23, v37
	v_cmp_lt_i32_e64 s[70:71], -1, v23
	v_cmp_gt_i32_e64 s[72:73], s7, v23
	s_and_b64 s[70:71], s[70:71], s[72:73]
	v_or_b32_e32 v160, v160, v10
	v_cndmask_b32_e64 v23, 0, v23, s[70:71]
	v_lshlrev_b64 v[160:161], 1, v[160:161]
	v_lshlrev_b32_e32 v23, s9, v23
	v_lshl_add_u64 v[176:177], s[24:25], 0, v[160:161]
	v_lshl_add_u64 v[160:161], s[26:27], 0, v[160:161]
	v_add_u32_e32 v23, s8, v23
	global_load_dwordx4 v[194:197], v[176:177], off offset:2048
	global_load_dwordx4 v[198:201], v[160:161], off
	v_mad_u64_u32 v[160:161], s[72:73], v23, s94, 0
	v_add_u32_e32 v23, s23, v38
	v_cmp_lt_i32_e64 s[72:73], -1, v23
	v_cmp_gt_i32_e64 s[74:75], s7, v23
	s_and_b64 s[72:73], s[72:73], s[74:75]
	v_or_b32_e32 v160, v160, v10
	v_cndmask_b32_e64 v23, 0, v23, s[72:73]
	v_lshlrev_b64 v[160:161], 1, v[160:161]
	v_lshlrev_b32_e32 v23, s9, v23
	v_lshl_add_u64 v[176:177], s[24:25], 0, v[160:161]
	v_lshl_add_u64 v[160:161], s[26:27], 0, v[160:161]
	v_add_u32_e32 v23, s8, v23
	global_load_dwordx4 v[202:205], v[176:177], off offset:2048
	global_load_dwordx4 v[206:209], v[160:161], off
	v_mad_u64_u32 v[160:161], s[74:75], v23, s94, 0
	v_add_u32_e32 v23, s23, v39
	v_cmp_lt_i32_e64 s[74:75], -1, v23
	v_cmp_gt_i32_e64 s[76:77], s7, v23
	s_and_b64 s[74:75], s[74:75], s[76:77]
	v_or_b32_e32 v160, v160, v10
	v_cndmask_b32_e64 v23, 0, v23, s[74:75]
	v_lshlrev_b64 v[160:161], 1, v[160:161]
	v_lshlrev_b32_e32 v23, s9, v23
	v_lshl_add_u64 v[176:177], s[24:25], 0, v[160:161]
	v_lshl_add_u64 v[160:161], s[26:27], 0, v[160:161]
	v_add_u32_e32 v23, s8, v23
	global_load_dwordx4 v[216:219], v[176:177], off offset:2048
	global_load_dwordx4 v[230:233], v[160:161], off
	v_mad_u64_u32 v[160:161], s[76:77], v23, s94, 0
	v_or_b32_e32 v160, v160, v10
	v_lshlrev_b64 v[160:161], 1, v[160:161]
	v_lshl_add_u64 v[176:177], s[26:27], 0, v[160:161]
	v_lshl_add_u64 v[160:161], s[24:25], 0, v[160:161]
	global_load_dwordx4 v[234:237], v[176:177], off
	global_load_dwordx4 v[238:241], v[160:161], off offset:2048
	v_add_u32_e32 v23, v11, v40
	s_mov_b32 s1, 0xf149f2ca
	s_waitcnt vmcnt(15)
	v_cndmask_b32_e32 v5, 0, v5, vcc
	v_cndmask_b32_e32 v4, 0, v4, vcc
	v_cndmask_b32_e32 v3, 0, v3, vcc
	v_cndmask_b32_e32 v2, 0, v2, vcc
	s_waitcnt vmcnt(14)
	v_cndmask_b32_e32 v9, 0, v9, vcc
	v_cndmask_b32_e32 v8, 0, v8, vcc
	v_cndmask_b32_e32 v7, 0, v7, vcc
	v_cndmask_b32_e32 v6, 0, v6, vcc
	ds_write_b128 v23, v[2:5]
	v_add_u32_e32 v2, v28, v40
	s_waitcnt vmcnt(13)
	v_cndmask_b32_e64 v27, 0, v27, s[62:63]
	v_cndmask_b32_e64 v26, 0, v26, s[62:63]
	v_cndmask_b32_e64 v25, 0, v25, s[62:63]
	v_cndmask_b32_e64 v24, 0, v24, s[62:63]
	ds_write_b128 v2, v[6:9]
	v_add_u32_e32 v2, v11, v41
	s_waitcnt vmcnt(12)
	v_cndmask_b32_e64 v159, 0, v159, s[62:63]
	v_cndmask_b32_e64 v158, 0, v158, s[62:63]
	v_cndmask_b32_e64 v157, 0, v157, s[62:63]
	v_cndmask_b32_e64 v156, 0, v156, s[62:63]
	ds_write_b128 v2, v[24:27]
	v_add_u32_e32 v2, v28, v41
	s_waitcnt vmcnt(11)
	v_cndmask_b32_e64 v181, 0, v181, s[64:65]
	v_cndmask_b32_e64 v180, 0, v180, s[64:65]
	v_cndmask_b32_e64 v179, 0, v179, s[64:65]
	v_cndmask_b32_e64 v178, 0, v178, s[64:65]
	ds_write_b128 v2, v[156:159]
	v_add_u32_e32 v2, v11, v42
	s_waitcnt vmcnt(10)
	v_cndmask_b32_e64 v185, 0, v185, s[64:65]
	v_cndmask_b32_e64 v184, 0, v184, s[64:65]
	v_cndmask_b32_e64 v183, 0, v183, s[64:65]
	v_cndmask_b32_e64 v182, 0, v182, s[64:65]
	ds_write_b128 v2, v[178:181]
	v_add_u32_e32 v2, v28, v42
	s_waitcnt vmcnt(9)
	v_cndmask_b32_e64 v189, 0, v189, s[66:67]
	v_cndmask_b32_e64 v188, 0, v188, s[66:67]
	v_cndmask_b32_e64 v187, 0, v187, s[66:67]
	v_cndmask_b32_e64 v186, 0, v186, s[66:67]
	ds_write_b128 v2, v[182:185]
	v_add_u32_e32 v242, s22, v29
	v_ashrrev_i32_e32 v243, 31, v242
	v_lshlrev_b64 v[242:243], s9, v[242:243]
	s_mov_b32 s9, s5
	v_lshl_add_u64 v[24:25], v[242:243], 0, s[8:9]
	v_mov_b64_e32 v[242:243], s[24:25]
	v_mad_u64_u32 v[242:243], s[8:9], v24, s86, v[242:243]
	v_mov_b32_e32 v246, v243
	v_mad_u64_u32 v[246:247], s[8:9], v25, s86, v[246:247]
	v_mov_b32_e32 v243, v246
	v_lshl_add_u64 v[242:243], v[242:243], 0, v[0:1]
	global_load_dwordx4 v[248:251], v[242:243], off
	global_load_dwordx4 v[156:159], v[242:243], off offset:64
	global_load_dwordx4 v[178:181], v[242:243], off offset:128
	global_load_dwordx4 v[182:185], v[242:243], off offset:192
	v_add_u32_e32 v2, v11, v43
	s_waitcnt vmcnt(12)
	v_cndmask_b32_e64 v193, 0, v193, s[66:67]
	v_cndmask_b32_e64 v192, 0, v192, s[66:67]
	v_cndmask_b32_e64 v191, 0, v191, s[66:67]
	v_cndmask_b32_e64 v190, 0, v190, s[66:67]
	ds_write_b128 v2, v[186:189]
	v_add_u32_e32 v2, v28, v43
	s_waitcnt vmcnt(11)
	v_cndmask_b32_e64 v197, 0, v197, s[68:69]
	v_cndmask_b32_e64 v196, 0, v196, s[68:69]
	v_cndmask_b32_e64 v195, 0, v195, s[68:69]
	v_cndmask_b32_e64 v194, 0, v194, s[68:69]
	ds_write_b128 v2, v[190:193]
	v_add_u32_e32 v2, v11, v44
	s_waitcnt vmcnt(10)
	v_cndmask_b32_e64 v201, 0, v201, s[68:69]
	v_cndmask_b32_e64 v200, 0, v200, s[68:69]
	v_cndmask_b32_e64 v199, 0, v199, s[68:69]
	v_cndmask_b32_e64 v198, 0, v198, s[68:69]
	ds_write_b128 v2, v[194:197]
	v_add_u32_e32 v2, v28, v44
	s_waitcnt vmcnt(9)
	v_cndmask_b32_e64 v205, 0, v205, s[70:71]
	v_cndmask_b32_e64 v204, 0, v204, s[70:71]
	v_cndmask_b32_e64 v203, 0, v203, s[70:71]
	v_cndmask_b32_e64 v202, 0, v202, s[70:71]
	ds_write_b128 v2, v[198:201]
	v_add_u32_e32 v2, v11, v45
	s_waitcnt vmcnt(8)
	v_cndmask_b32_e64 v209, 0, v209, s[70:71]
	v_cndmask_b32_e64 v208, 0, v208, s[70:71]
	v_cndmask_b32_e64 v207, 0, v207, s[70:71]
	v_cndmask_b32_e64 v206, 0, v206, s[70:71]
	ds_write_b128 v2, v[202:205]
	v_add_u32_e32 v2, v28, v45
	s_waitcnt vmcnt(7)
	v_cndmask_b32_e64 v219, 0, v219, s[72:73]
	v_cndmask_b32_e64 v218, 0, v218, s[72:73]
	v_cndmask_b32_e64 v217, 0, v217, s[72:73]
	v_cndmask_b32_e64 v216, 0, v216, s[72:73]
	ds_write_b128 v2, v[206:209]
	v_add_u32_e32 v2, v11, v46
	s_waitcnt vmcnt(6)
	v_cndmask_b32_e64 v233, 0, v233, s[72:73]
	v_cndmask_b32_e64 v232, 0, v232, s[72:73]
	v_cndmask_b32_e64 v231, 0, v231, s[72:73]
	v_cndmask_b32_e64 v230, 0, v230, s[72:73]
	ds_write_b128 v2, v[216:219]
	v_add_u32_e32 v2, v28, v46
	s_waitcnt vmcnt(4)
	v_cndmask_b32_e64 v241, 0, v241, s[74:75]
	v_cndmask_b32_e64 v240, 0, v240, s[74:75]
	v_cndmask_b32_e64 v239, 0, v239, s[74:75]
	v_cndmask_b32_e64 v238, 0, v238, s[74:75]
	ds_write_b128 v2, v[230:233]
	v_add_u32_e32 v2, v11, v47
	v_add_u32_e32 v26, s22, v29
	v_cndmask_b32_e64 v237, 0, v237, s[74:75]
	v_cndmask_b32_e64 v236, 0, v236, s[74:75]
	v_cndmask_b32_e64 v235, 0, v235, s[74:75]
	v_cndmask_b32_e64 v234, 0, v234, s[74:75]
	ds_write_b128 v2, v[238:241]
	v_add_u32_e32 v2, v28, v47
	v_ashrrev_i32_e32 v27, 31, v26
	ds_write_b128 v2, v[234:237]
	s_waitcnt lgkmcnt(0)
	s_barrier
	ds_read_b128 v[6:9], v146
	ds_read_b128 v[186:189], v146 offset:64
	s_waitcnt vmcnt(3) lgkmcnt(1)
	v_mfma_f32_16x16x32_bf16 v[6:9], v[6:9], v[248:251], 0
	ds_read_b128 v[190:193], v146 offset:128
	ds_read_b128 v[194:197], v147 offset:128
	ds_read_b128 v[198:201], v148 offset:128
	s_waitcnt vmcnt(2) lgkmcnt(3)
	v_mfma_f32_16x16x32_bf16 v[6:9], v[186:189], v[156:159], v[6:9]
	ds_read_b128 v[186:189], v146 offset:192
	ds_read_b128 v[202:205], v149 offset:128
	ds_read_b128 v[206:209], v150 offset:128
	s_waitcnt vmcnt(1) lgkmcnt(5)
	v_mfma_f32_16x16x32_bf16 v[6:9], v[190:193], v[178:181], v[6:9]
	ds_read_b128 v[190:193], v147
	ds_read_b128 v[216:219], v151 offset:128
	ds_read_b128 v[230:233], v152 offset:128
	s_waitcnt vmcnt(0) lgkmcnt(5)
	v_mfma_f32_16x16x32_bf16 v[186:189], v[186:189], v[182:185], v[6:9]
	ds_read_b128 v[234:237], v153 offset:128
	v_add_u32_e32 v23, v26, v30
	v_cmp_lt_i32_e32 vcc, -1, v23
	ds_read_b128 v[6:9], v147 offset:64
	s_waitcnt lgkmcnt(4)
	v_mfma_f32_16x16x32_bf16 v[190:193], v[190:193], v[248:251], 0
	s_and_b64 s[8:9], s[42:43], vcc
	v_cmp_gt_i32_e32 vcc, s7, v23
	v_mul_f32_e32 v23, 0x3db504f3, v186
	s_waitcnt lgkmcnt(0)
	v_mfma_f32_16x16x32_bf16 v[6:9], v[6:9], v[156:159], v[190:193]
	s_nop 2
	ds_read_b128 v[190:193], v147 offset:192
	s_and_b64 vcc, s[8:9], vcc
	v_add_u32_e32 v27, v49, v26
	v_mfma_f32_16x16x32_bf16 v[6:9], v[194:197], v[178:181], v[6:9]
	ds_read_b128 v[194:197], v148
	v_cndmask_b32_e32 v23, v214, v23, vcc
	v_cmp_lt_i32_e32 vcc, -1, v27
	s_waitcnt lgkmcnt(1)
	v_mfma_f32_16x16x32_bf16 v[190:193], v[190:193], v[182:185], v[6:9]
	s_and_b64 s[8:9], s[44:45], vcc
	s_nop 1
	ds_read_b128 v[6:9], v148 offset:64
	v_cmp_gt_i32_e32 vcc, s7, v27
	s_waitcnt lgkmcnt(1)
	v_mfma_f32_16x16x32_bf16 v[194:197], v[194:197], v[248:251], 0
	v_mul_f32_e32 v27, 0x3db504f3, v187
	s_and_b64 vcc, s[8:9], vcc
	v_cndmask_b32_e32 v27, v214, v27, vcc
	s_waitcnt lgkmcnt(0)
	v_mfma_f32_16x16x32_bf16 v[6:9], v[6:9], v[156:159], v[194:197]
	v_add_u32_e32 v160, v57, v26
	s_nop 1
	ds_read_b128 v[194:197], v148 offset:192
	v_add_u32_e32 v161, v58, v26
	v_mfma_f32_16x16x32_bf16 v[6:9], v[198:201], v[178:181], v[6:9]
	ds_read_b128 v[198:201], v149
	v_add_u32_e32 v168, v59, v26
	v_add_u32_e32 v169, v60, v26
	s_waitcnt lgkmcnt(1)
	v_mfma_f32_16x16x32_bf16 v[194:197], v[194:197], v[182:185], v[6:9]
	v_add_u32_e32 v176, v61, v26
	s_nop 1
	ds_read_b128 v[6:9], v149 offset:64
	v_add_u32_e32 v177, v62, v26
	s_waitcnt lgkmcnt(1)
	v_mfma_f32_16x16x32_bf16 v[198:201], v[198:201], v[248:251], 0
	v_max3_f32 v155, v23, s1, v27
	s_waitcnt lgkmcnt(0)
	v_mfma_f32_16x16x32_bf16 v[6:9], v[6:9], v[156:159], v[198:201]
	s_nop 4
	ds_read_b128 v[198:201], v149 offset:192
	v_mfma_f32_16x16x32_bf16 v[6:9], v[202:205], v[178:181], v[6:9]
	ds_read_b128 v[202:205], v150
	s_waitcnt lgkmcnt(1)
	v_mfma_f32_16x16x32_bf16 v[198:201], v[198:201], v[182:185], v[6:9]
	s_nop 4
	ds_read_b128 v[6:9], v150 offset:64
	s_waitcnt lgkmcnt(1)
	v_mfma_f32_16x16x32_bf16 v[202:205], v[202:205], v[248:251], 0
	s_waitcnt lgkmcnt(0)
	v_mfma_f32_16x16x32_bf16 v[6:9], v[6:9], v[156:159], v[202:205]
	s_nop 5
	ds_read_b128 v[202:205], v150 offset:192
	v_mfma_f32_16x16x32_bf16 v[6:9], v[206:209], v[178:181], v[6:9]
	ds_read_b128 v[206:209], v151
	s_waitcnt lgkmcnt(1)
	v_mfma_f32_16x16x32_bf16 v[202:205], v[202:205], v[182:185], v[6:9]
	s_nop 4
	ds_read_b128 v[6:9], v151 offset:64
	s_waitcnt lgkmcnt(1)
	v_mfma_f32_16x16x32_bf16 v[206:209], v[206:209], v[248:251], 0
	s_waitcnt lgkmcnt(0)
	v_mfma_f32_16x16x32_bf16 v[6:9], v[6:9], v[156:159], v[206:209]
	s_nop 5
	ds_read_b128 v[206:209], v151 offset:192
	v_mfma_f32_16x16x32_bf16 v[6:9], v[216:219], v[178:181], v[6:9]
	ds_read_b128 v[216:219], v152
	s_waitcnt lgkmcnt(1)
	v_mfma_f32_16x16x32_bf16 v[206:209], v[206:209], v[182:185], v[6:9]
	s_nop 4
	ds_read_b128 v[6:9], v152 offset:64
	s_waitcnt lgkmcnt(1)
	v_mfma_f32_16x16x32_bf16 v[216:219], v[216:219], v[248:251], 0
	s_waitcnt lgkmcnt(0)
	v_mfma_f32_16x16x32_bf16 v[6:9], v[6:9], v[156:159], v[216:219]
	s_nop 5
	ds_read_b128 v[216:219], v152 offset:192
	v_mfma_f32_16x16x32_bf16 v[6:9], v[230:233], v[178:181], v[6:9]
	ds_read_b128 v[230:233], v153
	s_waitcnt lgkmcnt(1)
	v_mfma_f32_16x16x32_bf16 v[216:219], v[216:219], v[182:185], v[6:9]
	s_nop 4
	ds_read_b128 v[6:9], v153 offset:64
	s_waitcnt lgkmcnt(1)
	v_mfma_f32_16x16x32_bf16 v[230:233], v[230:233], v[248:251], 0
	s_waitcnt lgkmcnt(0)
	v_mfma_f32_16x16x32_bf16 v[6:9], v[6:9], v[156:159], v[230:233]
	s_nop 5
	ds_read_b128 v[230:233], v153 offset:192
	v_mfma_f32_16x16x32_bf16 v[6:9], v[234:237], v[178:181], v[6:9]
	ds_read_b128 v[234:237], v154
	s_waitcnt lgkmcnt(1)
	v_mfma_f32_16x16x32_bf16 v[6:9], v[230:233], v[182:185], v[6:9]
	ds_read_b128 v[230:233], v154 offset:64
	s_waitcnt lgkmcnt(1)
	v_mfma_f32_16x16x32_bf16 v[2:5], v[234:237], v[248:251], 0
	ds_read_b128 v[234:237], v154 offset:128
	s_nop 3
	v_mul_f32_e32 v6, 0x3db504f3, v6
	s_waitcnt lgkmcnt(1)
	v_mfma_f32_16x16x32_bf16 v[2:5], v[230:233], v[156:159], v[2:5]
	ds_read_b128 v[156:159], v154 offset:192
	s_waitcnt lgkmcnt(1)
	v_mfma_f32_16x16x32_bf16 v[2:5], v[234:237], v[178:181], v[2:5]
	v_add_u32_e32 v178, v63, v26
	v_add_u32_e32 v179, v64, v26
	v_add_u32_e32 v180, v65, v26
	s_waitcnt lgkmcnt(0)
	v_mfma_f32_16x16x32_bf16 v[2:5], v[156:159], v[182:185], v[2:5]
	v_add_u32_e32 v156, v51, v26
	v_cmp_lt_i32_e32 vcc, -1, v156
	s_and_b64 s[8:9], s[46:47], vcc
	v_cmp_gt_i32_e32 vcc, s7, v156
	v_mul_f32_e32 v156, 0x3db504f3, v188
	s_and_b64 vcc, s[8:9], vcc
	v_add_u32_e32 v157, v53, v26
	v_cndmask_b32_e32 v156, v214, v156, vcc
	v_cmp_lt_i32_e32 vcc, -1, v157
	s_and_b64 s[8:9], s[48:49], vcc
	v_cmp_gt_i32_e32 vcc, s7, v157
	v_mul_f32_e32 v157, 0x3db504f3, v189
	s_and_b64 vcc, s[8:9], vcc
	v_add_u32_e32 v158, v55, v26
	v_cndmask_b32_e32 v157, v214, v157, vcc
	v_cmp_lt_i32_e32 vcc, -1, v158
	v_cmp_gt_i32_e64 s[62:63], s7, v158
	v_mul_f32_e32 v158, 0x3db504f3, v190
	s_and_b64 vcc, vcc, s[62:63]
	v_add_u32_e32 v159, v56, v26
	v_cndmask_b32_e32 v158, v214, v158, vcc
	v_cmp_lt_i32_e32 vcc, -1, v159
	v_cmp_gt_i32_e64 s[62:63], s7, v159
	v_mul_f32_e32 v159, 0x3db504f3, v191
	s_and_b64 vcc, vcc, s[62:63]
	v_cndmask_b32_e32 v159, v214, v159, vcc
	v_cmp_lt_i32_e32 vcc, -1, v160
	v_cmp_gt_i32_e64 s[62:63], s7, v160
	v_mul_f32_e32 v160, 0x3db504f3, v192
	s_and_b64 vcc, vcc, s[62:63]
	v_cndmask_b32_e32 v160, v214, v160, vcc
	v_cmp_lt_i32_e32 vcc, -1, v161
	v_cmp_gt_i32_e64 s[62:63], s7, v161
	v_mul_f32_e32 v161, 0x3db504f3, v193
	s_and_b64 vcc, vcc, s[62:63]
	v_cndmask_b32_e32 v161, v214, v161, vcc
	v_cmp_lt_i32_e32 vcc, -1, v168
	v_cmp_gt_i32_e64 s[62:63], s7, v168
	v_mul_f32_e32 v168, 0x3db504f3, v194
	s_and_b64 vcc, vcc, s[62:63]
	v_cndmask_b32_e32 v168, v214, v168, vcc
	v_cmp_lt_i32_e32 vcc, -1, v169
	v_cmp_gt_i32_e64 s[62:63], s7, v169
	v_mul_f32_e32 v169, 0x3db504f3, v195
	s_and_b64 vcc, vcc, s[62:63]
	v_cndmask_b32_e32 v169, v214, v169, vcc
	v_cmp_lt_i32_e32 vcc, -1, v176
	v_cmp_gt_i32_e64 s[62:63], s7, v176
	v_mul_f32_e32 v176, 0x3db504f3, v196
	s_and_b64 vcc, vcc, s[62:63]
	v_cndmask_b32_e32 v176, v214, v176, vcc
	v_cmp_lt_i32_e32 vcc, -1, v177
	v_cmp_gt_i32_e64 s[62:63], s7, v177
	v_mul_f32_e32 v177, 0x3db504f3, v197
	s_and_b64 vcc, vcc, s[62:63]
	v_cndmask_b32_e32 v177, v214, v177, vcc
	v_cmp_lt_i32_e32 vcc, -1, v178
	v_cmp_gt_i32_e64 s[62:63], s7, v178
	v_mul_f32_e32 v178, 0x3db504f3, v198
	s_and_b64 vcc, vcc, s[62:63]
	v_cndmask_b32_e32 v178, v214, v178, vcc
	v_cmp_lt_i32_e32 vcc, -1, v179
	v_cmp_gt_i32_e64 s[62:63], s7, v179
	v_mul_f32_e32 v179, 0x3db504f3, v199
	s_and_b64 vcc, vcc, s[62:63]
	v_cndmask_b32_e32 v179, v214, v179, vcc
	v_cmp_lt_i32_e32 vcc, -1, v180
	v_cmp_gt_i32_e64 s[62:63], s7, v180
	v_mul_f32_e32 v180, 0x3db504f3, v200
	s_and_b64 vcc, vcc, s[62:63]
	v_add_u32_e32 v181, v66, v26
	v_cndmask_b32_e32 v180, v214, v180, vcc
	v_cmp_lt_i32_e32 vcc, -1, v181
	v_cmp_gt_i32_e64 s[62:63], s7, v181
	v_mul_f32_e32 v181, 0x3db504f3, v201
	s_and_b64 vcc, vcc, s[62:63]
	v_add_u32_e32 v182, v26, v48
	v_cndmask_b32_e32 v181, v214, v181, vcc
	v_cmp_lt_i32_e32 vcc, -1, v182
	v_cmp_gt_i32_e64 s[62:63], s7, v182
	v_mul_f32_e32 v182, 0x3db504f3, v202
	s_and_b64 vcc, vcc, s[62:63]
	v_add_u32_e32 v183, v26, v50
	v_cndmask_b32_e32 v182, v214, v182, vcc
	v_cmp_lt_i32_e32 vcc, -1, v183
	v_cmp_gt_i32_e64 s[62:63], s7, v183
	v_mul_f32_e32 v183, 0x3db504f3, v203
	s_and_b64 vcc, vcc, s[62:63]
	v_add_u32_e32 v184, v26, v52
	v_cndmask_b32_e32 v183, v214, v183, vcc
	v_cmp_lt_i32_e32 vcc, -1, v184
	v_cmp_gt_i32_e64 s[62:63], s7, v184
	v_mul_f32_e32 v184, 0x3db504f3, v204
	s_and_b64 vcc, vcc, s[62:63]
	v_add_u32_e32 v185, v26, v54
	v_cndmask_b32_e32 v184, v214, v184, vcc
	v_cmp_lt_i32_e32 vcc, -1, v185
	v_cmp_gt_i32_e64 s[62:63], s7, v185
	v_mul_f32_e32 v185, 0x3db504f3, v205
	s_and_b64 vcc, vcc, s[62:63]
	v_cndmask_b32_e32 v190, v214, v185, vcc
	v_add_u32_e32 v185, v67, v26
	v_cmp_lt_i32_e32 vcc, -1, v185
	v_cmp_gt_i32_e64 s[62:63], s7, v185
	v_mul_f32_e32 v185, 0x3db504f3, v206
	s_and_b64 vcc, vcc, s[62:63]
	v_cndmask_b32_e32 v191, v214, v185, vcc
	v_add_u32_e32 v185, v68, v26
	v_cmp_lt_i32_e32 vcc, -1, v185
	v_cmp_gt_i32_e64 s[62:63], s7, v185
	v_mul_f32_e32 v185, 0x3db504f3, v207
	s_and_b64 vcc, vcc, s[62:63]
	v_cndmask_b32_e32 v206, v214, v185, vcc
	v_add_u32_e32 v185, v69, v26
	v_cmp_lt_i32_e32 vcc, -1, v185
	v_cmp_gt_i32_e64 s[62:63], s7, v185
	v_mul_f32_e32 v185, 0x3db504f3, v208
	s_and_b64 vcc, vcc, s[62:63]
	v_cndmask_b32_e32 v207, v214, v185, vcc
	v_add_u32_e32 v185, v70, v26
	v_cmp_lt_i32_e32 vcc, -1, v185
	v_cmp_gt_i32_e64 s[62:63], s7, v185
	v_mul_f32_e32 v185, 0x3db504f3, v209
	s_and_b64 vcc, vcc, s[62:63]
	v_cndmask_b32_e32 v208, v214, v185, vcc
	v_add_u32_e32 v185, v71, v26
	v_cmp_lt_i32_e32 vcc, -1, v185
	v_cmp_gt_i32_e64 s[62:63], s7, v185
	v_mul_f32_e32 v185, 0x3db504f3, v216
	s_and_b64 vcc, vcc, s[62:63]
	v_cndmask_b32_e32 v220, v214, v185, vcc
	v_add_u32_e32 v185, v72, v26
	v_cmp_lt_i32_e32 vcc, -1, v185
	v_cmp_gt_i32_e64 s[62:63], s7, v185
	v_mul_f32_e32 v185, 0x3db504f3, v217
	s_and_b64 vcc, vcc, s[62:63]
	v_cndmask_b32_e32 v221, v214, v185, vcc
	v_add_u32_e32 v185, v73, v26
	v_cmp_lt_i32_e32 vcc, -1, v185
	v_cmp_gt_i32_e64 s[62:63], s7, v185
	v_mul_f32_e32 v185, 0x3db504f3, v218
	s_and_b64 vcc, vcc, s[62:63]
	v_cndmask_b32_e32 v238, v214, v185, vcc
	v_add_u32_e32 v185, v74, v26
	v_cmp_lt_i32_e32 vcc, -1, v185
	v_cmp_gt_i32_e64 s[62:63], s7, v185
	v_mul_f32_e32 v185, 0x3db504f3, v219
	s_and_b64 vcc, vcc, s[62:63]
	v_cndmask_b32_e32 v239, v214, v185, vcc
	v_add_u32_e32 v185, v26, v75
	v_cmp_lt_i32_e32 vcc, -1, v185
	v_cmp_gt_i32_e64 s[62:63], s7, v185
	s_and_b64 vcc, vcc, s[62:63]
	v_cndmask_b32_e32 v240, v214, v6, vcc
	v_add_u32_e32 v6, v76, v26
	v_max3_f32 v155, v155, v156, v157
	v_cmp_lt_i32_e32 vcc, -1, v6
	v_cmp_gt_i32_e64 s[62:63], s7, v6
	v_max3_f32 v155, v155, v158, v159
	v_mul_f32_e32 v6, 0x3db504f3, v7
	s_and_b64 vcc, vcc, s[62:63]
	v_add_u32_e32 v7, v77, v26
	v_max3_f32 v155, v155, v160, v161
	v_cndmask_b32_e32 v241, v214, v6, vcc
	v_cmp_lt_i32_e32 vcc, -1, v7
	v_max3_f32 v155, v155, v168, v169
	s_and_b64 s[8:9], s[50:51], vcc
	v_cmp_gt_i32_e32 vcc, s7, v7
	v_max3_f32 v155, v155, v176, v177
	v_mul_f32_e32 v7, 0x3db504f3, v8
	s_and_b64 vcc, s[8:9], vcc
	v_max3_f32 v155, v155, v178, v179
	v_cndmask_b32_e32 v8, v214, v7, vcc
	v_add_u32_e32 v7, v78, v26
	v_max3_f32 v155, v155, v180, v181
	v_cmp_lt_i32_e32 vcc, -1, v7
	v_max3_f32 v155, v155, v182, v183
	s_and_b64 s[8:9], s[52:53], vcc
	v_cmp_gt_i32_e32 vcc, s7, v7
	v_max3_f32 v155, v155, v184, v190
	v_mul_f32_e32 v7, 0x3db504f3, v9
	s_and_b64 vcc, s[8:9], vcc
	v_max3_f32 v155, v155, v191, v206
	v_cndmask_b32_e32 v9, v214, v7, vcc
	v_add_u32_e32 v7, v79, v26
	v_max3_f32 v155, v155, v207, v208
	v_cmp_lt_i32_e32 vcc, -1, v7
	v_max3_f32 v155, v155, v220, v221
	s_and_b64 s[8:9], s[54:55], vcc
	v_cmp_gt_i32_e32 vcc, s7, v7
	v_max3_f32 v155, v155, v238, v239
	v_mul_f32_e32 v2, 0x3db504f3, v2
	s_and_b64 vcc, s[8:9], vcc
	v_max3_f32 v6, v155, v240, v241
	v_cndmask_b32_e32 v155, v214, v2, vcc
	v_add_u32_e32 v2, v80, v26
	v_cmp_lt_i32_e32 vcc, -1, v2
	s_and_b64 s[8:9], s[56:57], vcc
	v_cmp_gt_i32_e32 vcc, s7, v2
	v_mul_f32_e32 v2, 0x3db504f3, v3
	s_and_b64 vcc, s[8:9], vcc
	v_max3_f32 v6, v6, v8, v9
	v_cndmask_b32_e32 v3, v214, v2, vcc
	v_max3_f32 v2, v6, v155, v3
	v_add_u32_e32 v6, v81, v26
	v_cmp_lt_i32_e32 vcc, -1, v6
	s_and_b64 s[8:9], s[58:59], vcc
	v_cmp_gt_i32_e32 vcc, s7, v6
	v_mul_f32_e32 v4, 0x3db504f3, v4
	s_and_b64 vcc, s[8:9], vcc
	v_cndmask_b32_e32 v242, v214, v4, vcc
	v_add_u32_e32 v4, v82, v26
	v_cmp_lt_i32_e32 vcc, -1, v4
	s_and_b64 s[8:9], s[60:61], vcc
	v_cmp_gt_i32_e32 vcc, s7, v4
	v_mul_f32_e32 v4, 0x3db504f3, v5
	s_and_b64 vcc, s[8:9], vcc
	v_cndmask_b32_e32 v26, v214, v4, vcc
	v_max3_f32 v2, v2, v242, v26
	ds_bpermute_b32 v4, v31, v2
	s_cmp_eq_u32 s6, 1
	s_cselect_b32 s1, s30, s34
	s_cselect_b32 s7, s29, s31
	s_cmpk_lt_u32 s78, 0x200
	s_waitcnt lgkmcnt(0)
	v_max_f32_e32 v4, v4, v4
	v_max_f32_e32 v2, v2, v4
	ds_bpermute_b32 v4, v32, v2
	s_waitcnt lgkmcnt(0)
	v_max_f32_e32 v4, v4, v4
	v_max_f32_e32 v2, v2, v4
	v_sub_f32_e32 v7, v156, v2
	v_sub_f32_e32 v156, v159, v2
	v_sub_f32_e32 v159, v168, v2
	v_sub_f32_e32 v4, v23, v2
	v_mul_f32_e32 v159, 0x3fb8aa3b, v159
	v_mul_f32_e32 v4, 0x3fb8aa3b, v4
	v_sub_f32_e32 v5, v27, v2
	v_sub_f32_e32 v23, v157, v2
	v_sub_f32_e32 v157, v160, v2
	v_exp_f32_e32 v160, v159
	v_sub_f32_e32 v159, v169, v2
	v_exp_f32_e32 v4, v4
	v_mul_f32_e32 v5, 0x3fb8aa3b, v5
	v_mul_f32_e32 v159, 0x3fb8aa3b, v159
	v_exp_f32_e32 v5, v5
	v_mul_f32_e32 v7, 0x3fb8aa3b, v7
	v_sub_f32_e32 v27, v158, v2
	v_sub_f32_e32 v158, v161, v2
	v_exp_f32_e32 v161, v159
	v_sub_f32_e32 v159, v176, v2
	v_exp_f32_e32 v7, v7
	v_mul_f32_e32 v23, 0x3fb8aa3b, v23
	v_mul_f32_e32 v159, 0x3fb8aa3b, v159
	v_exp_f32_e32 v23, v23
	v_mul_f32_e32 v27, 0x3fb8aa3b, v27
	v_exp_f32_e32 v168, v159
	v_sub_f32_e32 v159, v177, v2
	v_add_f32_e32 v6, 0, v4
	v_exp_f32_e32 v27, v27
	v_mul_f32_e32 v156, 0x3fb8aa3b, v156
	v_mul_f32_e32 v159, 0x3fb8aa3b, v159
	v_add_f32_e32 v6, v5, v6
	v_exp_f32_e32 v156, v156
	v_mul_f32_e32 v157, 0x3fb8aa3b, v157
	v_exp_f32_e32 v169, v159
	v_sub_f32_e32 v159, v178, v2
	v_add_f32_e32 v6, v7, v6
	v_exp_f32_e32 v157, v157
	v_mul_f32_e32 v158, 0x3fb8aa3b, v158
	v_mul_f32_e32 v159, 0x3fb8aa3b, v159
	v_add_f32_e32 v6, v23, v6
	v_exp_f32_e32 v158, v158
	v_exp_f32_e32 v176, v159
	v_sub_f32_e32 v159, v179, v2
	v_add_f32_e32 v6, v27, v6
	v_mul_f32_e32 v159, 0x3fb8aa3b, v159
	v_add_f32_e32 v6, v156, v6
	v_exp_f32_e32 v177, v159
	v_sub_f32_e32 v159, v180, v2
	v_add_f32_e32 v6, v157, v6
	v_mul_f32_e32 v159, 0x3fb8aa3b, v159
	v_add_f32_e32 v6, v158, v6
	v_exp_f32_e32 v209, v159
	v_sub_f32_e32 v159, v181, v2
	v_add_f32_e32 v6, v160, v6
	v_mul_f32_e32 v159, 0x3fb8aa3b, v159
	v_add_f32_e32 v6, v161, v6
	v_exp_f32_e32 v216, v159
	v_sub_f32_e32 v159, v182, v2
	v_add_f32_e32 v6, v168, v6
	v_mul_f32_e32 v159, 0x3fb8aa3b, v159
	v_add_f32_e32 v6, v169, v6
	v_exp_f32_e32 v243, v159
	v_sub_f32_e32 v159, v183, v2
	v_add_f32_e32 v6, v176, v6
	v_mul_f32_e32 v159, 0x3fb8aa3b, v159
	v_add_f32_e32 v6, v177, v6
	v_exp_f32_e32 v244, v159
	v_add_f32_e32 v6, v209, v6
	v_add_f32_e32 v6, v216, v6
	v_add_f32_e32 v6, v243, v6
	v_add_f32_e32 v192, v244, v6
	v_sub_f32_e32 v6, v184, v2
	v_mul_f32_e32 v6, 0x3fb8aa3b, v6
	v_cvt_pk_bf16_f32 v4, v4, v5
	v_cvt_pk_bf16_f32 v5, v7, v23
	v_sub_f32_e32 v23, v190, v2
	v_exp_f32_e32 v245, v6
	v_cvt_pk_bf16_f32 v6, v27, v156
	v_mul_f32_e32 v23, 0x3fb8aa3b, v23
	v_sub_f32_e32 v27, v191, v2
	v_exp_f32_e32 v23, v23
	v_mul_f32_e32 v27, 0x3fb8aa3b, v27
	v_exp_f32_e32 v27, v27
	v_sub_f32_e32 v206, v206, v2
	v_mul_f32_e32 v206, 0x3fb8aa3b, v206
	v_add_f32_e32 v190, v245, v192
	v_exp_f32_e32 v247, v206
	v_sub_f32_e32 v206, v207, v2
	v_cvt_pk_bf16_f32 v7, v157, v158
	ds_read_b64_tr_b16 v[186:187], v14
	ds_read_b64_tr_b16 v[188:189], v15
	ds_read_b64_tr_b16 v[182:183], v83
	ds_read_b64_tr_b16 v[184:185], v84
	ds_read_b64_tr_b16 v[178:179], v85
	ds_read_b64_tr_b16 v[180:181], v86
	ds_read_b64_tr_b16 v[156:157], v87
	ds_read_b64_tr_b16 v[158:159], v88
	s_waitcnt lgkmcnt(0)
	v_add_f32_e32 v190, v23, v190
	v_mul_f32_e32 v206, 0x3fb8aa3b, v206
	v_add_f32_e32 v246, v27, v190
	ds_read_b64_tr_b16 v[202:203], v89
	ds_read_b64_tr_b16 v[204:205], v90
	ds_read_b64_tr_b16 v[198:199], v91
	ds_read_b64_tr_b16 v[200:201], v92
	ds_read_b64_tr_b16 v[194:195], v93
	ds_read_b64_tr_b16 v[196:197], v94
	ds_read_b64_tr_b16 v[190:191], v95
	ds_read_b64_tr_b16 v[192:193], v96
	s_waitcnt lgkmcnt(0)
	v_exp_f32_e32 v248, v206
	v_sub_f32_e32 v206, v208, v2
	v_mfma_f32_16x16x32_bf16 v[186:189], v[186:189], v[4:7], 0
	v_mul_f32_e32 v206, 0x3fb8aa3b, v206
	v_exp_f32_e32 v249, v206
	v_sub_f32_e32 v8, v8, v2
	v_mfma_f32_16x16x32_bf16 v[182:185], v[182:185], v[4:7], 0
	v_sub_f32_e32 v9, v9, v2
	v_mul_f32_e32 v8, 0x3fb8aa3b, v8
	v_mul_f32_e32 v9, 0x3fb8aa3b, v9
	v_mfma_f32_16x16x32_bf16 v[178:181], v[178:181], v[4:7], 0
	v_exp_f32_e32 v8, v8
	v_exp_f32_e32 v9, v9
	v_sub_f32_e32 v155, v155, v2
	v_mfma_f32_16x16x32_bf16 v[156:159], v[156:159], v[4:7], 0
	v_mul_f32_e32 v155, 0x3fb8aa3b, v155
	v_sub_f32_e32 v3, v3, v2
	v_exp_f32_e32 v155, v155
	v_mfma_f32_16x16x32_bf16 v[202:205], v[202:205], v[4:7], 0
	v_mul_f32_e32 v3, 0x3fb8aa3b, v3
	v_exp_f32_e32 v3, v3
	v_mfma_f32_16x16x32_bf16 v[198:201], v[198:201], v[4:7], 0
	v_mfma_f32_16x16x32_bf16 v[194:197], v[194:197], v[4:7], 0
	v_mfma_f32_16x16x32_bf16 v[4:7], v[190:193], v[4:7], 0
	v_cvt_pk_bf16_f32 v190, v160, v161
	v_sub_f32_e32 v161, v220, v2
	v_cvt_pk_bf16_f32 v191, v168, v169
	v_mul_f32_e32 v161, 0x3fb8aa3b, v161
	v_sub_f32_e32 v168, v221, v2
	v_exp_f32_e32 v161, v161
	v_mul_f32_e32 v168, 0x3fb8aa3b, v168
	v_sub_f32_e32 v169, v238, v2
	v_cvt_pk_bf16_f32 v192, v176, v177
	v_cvt_pk_bf16_f32 v193, v209, v216
	ds_read_b64_tr_b16 v[234:235], v16
	ds_read_b64_tr_b16 v[236:237], v17
	ds_read_b64_tr_b16 v[230:231], v97
	ds_read_b64_tr_b16 v[232:233], v98
	ds_read_b64_tr_b16 v[216:217], v99
	ds_read_b64_tr_b16 v[218:219], v100
	ds_read_b64_tr_b16 v[206:207], v101
	ds_read_b64_tr_b16 v[208:209], v102
	s_waitcnt lgkmcnt(0)
	v_add_f32_e32 v160, v247, v246
	v_exp_f32_e32 v168, v168
	v_mul_f32_e32 v169, 0x3fb8aa3b, v169
	v_sub_f32_e32 v176, v239, v2
	v_mfma_f32_16x16x32_bf16 v[186:189], v[234:237], v[190:193], v[186:189]
	v_add_f32_e32 v160, v248, v160
	v_exp_f32_e32 v169, v169
	v_mul_f32_e32 v176, 0x3fb8aa3b, v176
	v_mfma_f32_16x16x32_bf16 v[182:185], v[230:233], v[190:193], v[182:185]
	v_add_f32_e32 v160, v249, v160
	v_exp_f32_e32 v176, v176
	v_add_f32_e32 v160, v161, v160
	v_mfma_f32_16x16x32_bf16 v[178:181], v[216:219], v[190:193], v[178:181]
	v_add_f32_e32 v160, v168, v160
	v_add_f32_e32 v160, v169, v160
	v_add_f32_e32 v160, v176, v160
	v_mfma_f32_16x16x32_bf16 v[156:159], v[206:209], v[190:193], v[156:159]
	ds_read_b64_tr_b16 v[234:235], v103
	ds_read_b64_tr_b16 v[236:237], v104
	ds_read_b64_tr_b16 v[230:231], v105
	ds_read_b64_tr_b16 v[232:233], v106
	ds_read_b64_tr_b16 v[216:217], v107
	ds_read_b64_tr_b16 v[218:219], v108
	ds_read_b64_tr_b16 v[206:207], v109
	ds_read_b64_tr_b16 v[208:209], v110
	s_waitcnt lgkmcnt(0)
	s_nop 0
	v_mfma_f32_16x16x32_bf16 v[202:205], v[234:237], v[190:193], v[202:205]
	v_mfma_f32_16x16x32_bf16 v[198:201], v[230:233], v[190:193], v[198:201]
	v_mfma_f32_16x16x32_bf16 v[194:197], v[216:219], v[190:193], v[194:197]
	v_mfma_f32_16x16x32_bf16 v[4:7], v[206:209], v[190:193], v[4:7]
	v_cvt_pk_bf16_f32 v191, v245, v23
	v_sub_f32_e32 v23, v240, v2
	v_cvt_pk_bf16_f32 v192, v27, v247
	v_mul_f32_e32 v23, 0x3fb8aa3b, v23
	v_sub_f32_e32 v27, v241, v2
	v_exp_f32_e32 v23, v23
	v_mul_f32_e32 v27, 0x3fb8aa3b, v27
	v_exp_f32_e32 v27, v27
	v_cvt_pk_bf16_f32 v190, v243, v244
	v_add_f32_e32 v160, v23, v160
	v_cvt_pk_bf16_f32 v193, v248, v249
	ds_read_b64_tr_b16 v[234:235], v18
	ds_read_b64_tr_b16 v[236:237], v19
	ds_read_b64_tr_b16 v[230:231], v111
	ds_read_b64_tr_b16 v[232:233], v112
	ds_read_b64_tr_b16 v[216:217], v113
	ds_read_b64_tr_b16 v[218:219], v114
	ds_read_b64_tr_b16 v[206:207], v115
	ds_read_b64_tr_b16 v[208:209], v116
	s_waitcnt lgkmcnt(0)
	v_add_f32_e32 v160, v27, v160
	s_nop 0
	v_mfma_f32_16x16x32_bf16 v[186:189], v[234:237], v[190:193], v[186:189]
	v_mfma_f32_16x16x32_bf16 v[182:185], v[230:233], v[190:193], v[182:185]
	v_mfma_f32_16x16x32_bf16 v[178:181], v[216:219], v[190:193], v[178:181]
	v_mfma_f32_16x16x32_bf16 v[156:159], v[206:209], v[190:193], v[156:159]
	ds_read_b64_tr_b16 v[234:235], v117
	ds_read_b64_tr_b16 v[236:237], v118
	ds_read_b64_tr_b16 v[230:231], v119
	ds_read_b64_tr_b16 v[232:233], v120
	ds_read_b64_tr_b16 v[216:217], v121
	ds_read_b64_tr_b16 v[218:219], v122
	ds_read_b64_tr_b16 v[206:207], v123
	ds_read_b64_tr_b16 v[208:209], v124
	s_waitcnt lgkmcnt(0)
	s_nop 0
	v_mfma_f32_16x16x32_bf16 v[202:205], v[234:237], v[190:193], v[202:205]
	v_mfma_f32_16x16x32_bf16 v[198:201], v[230:233], v[190:193], v[198:201]
	v_mfma_f32_16x16x32_bf16 v[194:197], v[216:219], v[190:193], v[194:197]
	v_mfma_f32_16x16x32_bf16 v[4:7], v[206:209], v[190:193], v[4:7]
	v_cvt_pk_bf16_f32 v193, v8, v9
	v_add_f32_e32 v8, v8, v160
	v_add_f32_e32 v8, v9, v8
	v_sub_f32_e32 v9, v242, v2
	v_cvt_pk_bf16_f32 v192, v23, v27
	v_mul_f32_e32 v9, 0x3fb8aa3b, v9
	v_sub_f32_e32 v23, v26, v2
	v_exp_f32_e32 v9, v9
	v_mul_f32_e32 v23, 0x3fb8aa3b, v23
	v_exp_f32_e32 v23, v23
	v_add_f32_e32 v8, v155, v8
	v_add_f32_e32 v8, v3, v8
	v_add_f32_e32 v8, v9, v8
	v_add_f32_e32 v8, v23, v8
	ds_bpermute_b32 v26, v31, v8
	v_cvt_pk_bf16_f32 v190, v161, v168
	v_cvt_pk_bf16_f32 v191, v169, v176
	ds_read_b64_tr_b16 v[234:235], v20
	ds_read_b64_tr_b16 v[236:237], v21
	ds_read_b64_tr_b16 v[230:231], v125
	ds_read_b64_tr_b16 v[232:233], v126
	ds_read_b64_tr_b16 v[216:217], v127
	ds_read_b64_tr_b16 v[218:219], v128
	ds_read_b64_tr_b16 v[206:207], v129
	ds_read_b64_tr_b16 v[208:209], v130
	s_waitcnt lgkmcnt(0)
	v_cvt_pk_bf16_f32 v9, v9, v23
	s_waitcnt lgkmcnt(0)
	v_add_f32_e32 v160, v8, v26
	ds_bpermute_b32 v161, v32, v160
	v_mfma_f32_16x16x32_bf16 v[186:189], v[234:237], v[190:193], v[186:189]
	v_cvt_pk_bf16_f32 v8, v155, v3
	s_waitcnt lgkmcnt(0)
	v_add_f32_e32 v3, v160, v161
	v_mfma_f32_16x16x32_bf16 v[182:185], v[230:233], v[190:193], v[182:185]
	v_div_scale_f32 v23, s[8:9], v3, v3, 1.0
	v_rcp_f32_e32 v155, v23
	v_mfma_f32_16x16x32_bf16 v[178:181], v[216:219], v[190:193], v[178:181]
	s_cselect_b32 s9, s21, s7
	s_cselect_b32 s8, s28, s1
	v_mfma_f32_16x16x32_bf16 v[156:159], v[206:209], v[190:193], v[156:159]
	ds_read_b64_tr_b16 v[234:235], v131
	ds_read_b64_tr_b16 v[236:237], v132
	ds_read_b64_tr_b16 v[230:231], v133
	ds_read_b64_tr_b16 v[232:233], v134
	ds_read_b64_tr_b16 v[216:217], v135
	ds_read_b64_tr_b16 v[218:219], v136
	ds_read_b64_tr_b16 v[206:207], v137
	ds_read_b64_tr_b16 v[208:209], v138
	s_waitcnt lgkmcnt(0)
	ds_read_b64_tr_b16 v[26:27], v12
	s_waitcnt lgkmcnt(0)
	s_nop 0
	v_mfma_f32_16x16x32_bf16 v[202:205], v[234:237], v[190:193], v[202:205]
	v_mfma_f32_16x16x16_bf16 v[186:189], v[26:27], v[8:9], v[186:189]
	ds_read_b64_tr_b16 v[26:27], v139
	s_waitcnt lgkmcnt(0)
	v_mfma_f32_16x16x32_bf16 v[198:201], v[230:233], v[190:193], v[198:201]
	v_mfma_f32_16x16x16_bf16 v[182:185], v[26:27], v[8:9], v[182:185]
	ds_read_b64_tr_b16 v[26:27], v140
	s_waitcnt lgkmcnt(0)
	v_mfma_f32_16x16x32_bf16 v[194:197], v[216:219], v[190:193], v[194:197]
	v_mfma_f32_16x16x32_bf16 v[4:7], v[206:209], v[190:193], v[4:7]
	v_mfma_f32_16x16x16_bf16 v[178:181], v[26:27], v[8:9], v[178:181]
	ds_read_b64_tr_b16 v[26:27], v141
	s_waitcnt lgkmcnt(0)
	s_nop 0
	v_mfma_f32_16x16x16_bf16 v[156:159], v[26:27], v[8:9], v[156:159]
	ds_read_b64_tr_b16 v[26:27], v142
	s_waitcnt lgkmcnt(0)
	s_nop 0
	v_mfma_f32_16x16x16_bf16 v[190:193], v[26:27], v[8:9], v[202:205]
	ds_read_b64_tr_b16 v[26:27], v143
	s_waitcnt lgkmcnt(0)
	s_nop 0
	v_mfma_f32_16x16x16_bf16 v[198:201], v[26:27], v[8:9], v[198:201]
	ds_read_b64_tr_b16 v[26:27], v144
	s_waitcnt lgkmcnt(0)
	s_nop 0
	v_mfma_f32_16x16x16_bf16 v[194:197], v[26:27], v[8:9], v[194:197]
	ds_read_b64_tr_b16 v[26:27], v145
	s_waitcnt lgkmcnt(0)
	s_nop 0
	v_mfma_f32_16x16x16_bf16 v[4:7], v[26:27], v[8:9], v[4:7]
	v_fma_f32 v8, -v23, v155, 1.0
	v_fmac_f32_e32 v155, v8, v155
	v_div_scale_f32 v8, vcc, 1.0, v3, 1.0
	v_mul_f32_e32 v9, v8, v155
	v_fma_f32 v26, -v23, v9, v8
	v_fmac_f32_e32 v9, v26, v155
	v_fma_f32 v8, -v23, v9, v8
	v_div_fmas_f32 v8, v8, v155, v9
	v_lshlrev_b64 v[26:27], 11, v[24:25]
	v_div_fixup_f32 v8, v8, v3, 1.0
	v_lshl_add_u64 v[26:27], s[8:9], 0, v[26:27]
	v_lshl_add_u64 v[26:27], v[26:27], 0, s[4:5]
	v_mov_b32_e32 v23, v1
	v_pk_mul_f32 v[158:159], v[158:159], v[8:9] op_sel_hi:[1,0]
	v_pk_mul_f32 v[156:157], v[156:157], v[8:9] op_sel_hi:[1,0]
	v_lshl_add_u64 v[26:27], v[26:27], 0, v[22:23]
	v_cvt_pk_bf16_f32 v156, v156, v157
	v_cvt_pk_bf16_f32 v157, v158, v159
	v_pk_mul_f32 v[160:161], v[188:189], v[8:9] op_sel_hi:[1,0]
	v_pk_mul_f32 v[176:177], v[186:187], v[8:9] op_sel_hi:[1,0]
	global_store_dwordx2 v[26:27], v[156:157], off offset:96
	v_pk_mul_f32 v[156:157], v[8:9], v[192:193] op_sel_hi:[0,1]
	v_pk_mul_f32 v[158:159], v[8:9], v[190:191] op_sel_hi:[0,1]
	v_cvt_pk_bf16_f32 v176, v176, v177
	v_cvt_pk_bf16_f32 v177, v160, v161
	v_cvt_pk_bf16_f32 v158, v158, v159
	v_cvt_pk_bf16_f32 v159, v156, v157
	global_store_dwordx2 v[26:27], v[176:177], off
	v_pk_mul_f32 v[160:161], v[184:185], v[8:9] op_sel_hi:[1,0]
	v_pk_mul_f32 v[176:177], v[182:183], v[8:9] op_sel_hi:[1,0]
	global_store_dwordx2 v[26:27], v[158:159], off offset:128
	v_pk_mul_f32 v[156:157], v[8:9], v[200:201] op_sel_hi:[0,1]
	v_pk_mul_f32 v[158:159], v[8:9], v[198:199] op_sel_hi:[0,1]
	v_cvt_pk_bf16_f32 v176, v176, v177
	v_cvt_pk_bf16_f32 v177, v160, v161
	v_cvt_pk_bf16_f32 v158, v158, v159
	v_cvt_pk_bf16_f32 v159, v156, v157
	global_store_dwordx2 v[26:27], v[176:177], off offset:32
	v_pk_mul_f32 v[160:161], v[180:181], v[8:9] op_sel_hi:[1,0]
	v_pk_mul_f32 v[176:177], v[178:179], v[8:9] op_sel_hi:[1,0]
	global_store_dwordx2 v[26:27], v[158:159], off offset:160
	v_pk_mul_f32 v[156:157], v[8:9], v[196:197] op_sel_hi:[0,1]
	v_pk_mul_f32 v[158:159], v[8:9], v[194:195] op_sel_hi:[0,1]
	v_pk_mul_f32 v[6:7], v[8:9], v[6:7] op_sel_hi:[0,1]
	v_pk_mul_f32 v[4:5], v[8:9], v[4:5] op_sel_hi:[0,1]
	v_cvt_pk_bf16_f32 v176, v176, v177
	v_cvt_pk_bf16_f32 v177, v160, v161
	v_cvt_pk_bf16_f32 v158, v158, v159
	v_cvt_pk_bf16_f32 v159, v156, v157
	v_cvt_pk_bf16_f32 v4, v4, v5
	v_cvt_pk_bf16_f32 v5, v6, v7
	global_store_dwordx2 v[26:27], v[176:177], off offset:64
	global_store_dwordx2 v[26:27], v[158:159], off offset:192
	global_store_dwordx2 v[26:27], v[4:5], off offset:224
	s_and_saveexec_b64 s[8:9], s[40:41]
	s_cbranch_execz .LBB0_345
	v_cmp_gt_f32_e32 vcc, s39, v3
	s_mov_b32 s1, 0x3f317217
	s_ashr_i32 s7, s6, 31
	v_cndmask_b32_e64 v4, 0, 32, vcc
	v_ldexp_f32 v3, v3, v4
	v_log_f32_e32 v3, v3
	v_cndmask_b32_e32 v4, 0, v213, vcc
	s_lshl_b64 s[6:7], s[6:7], 18
	s_add_u32 s6, s37, s6
	v_mul_f32_e32 v5, 0x3f317217, v3
	v_fma_f32 v5, v3, s1, -v5
	v_fmac_f32_e32 v5, 0x3377d1cf, v3
	s_mov_b32 s1, 0x7f800000
	v_fmac_f32_e32 v5, 0x3f317217, v3
	v_cmp_lt_f32_e64 vcc, |v3|, s1
	s_addc_u32 s7, s36, s7
	s_lshl_b32 s4, s79, 2
	v_cndmask_b32_e32 v3, v3, v5, vcc
	v_sub_f32_e32 v3, v3, v4
	v_add_f32_e32 v4, v2, v3
	v_lshlrev_b64 v[2:3], 5, v[24:25]
	v_lshl_add_u64 v[2:3], s[6:7], 0, v[2:3]
	v_lshl_add_u64 v[2:3], v[2:3], 0, s[4:5]
	global_store_dword v[2:3], v4, off
	s_branch .LBB0_345
